# strategy 6: weight-conversion transpose tile re-laid out (row stride 289, column skew c + c>>5) so its LDS writes are conflict-free
# speedup vs baseline: 1.0041x; 1.0041x over previous
; #define LAS __attribute__((address_space(3)))
; __device__ __forceinline__ int tid_fresh() { int t = threadIdx.x; asm volatile("" : "+v"(t)); return t; }
; __device__ __forceinline__ int bid_fresh() { int b = blockIdx.x; asm volatile("" : "+s"(b)); return b; }
; __device__ __forceinline__ int gdim_fresh() { int g = gridDim.x; asm volatile("" : "+s"(g)); return g; }
; __device__ __forceinline__ void convert_phase(const Params& p, LAS unsigned char* lds) {
;     LAS float* tl = (LAS float*)lds;
;     const int tid = tid_fresh(), G = gdim_fresh(), bid = bid_fresh();
;     const int kr = tid >> 6, c4 = tid & 63;
;     f32x4 rg[8];
;     int tile = bid;
;     const float* src = nullptr; bf16_t* dst = nullptr; const float* gain = nullptr; int K = 0, N = 0, lt = 0, k0 = 0, n0 = 0;
;     bool have = tile < NT_CONV;
;     if (have) {
;         wjob(p, tile, src, dst, gain, K, N, lt);
;         const int nn = N >> 8; k0 = (lt / nn) * 64; n0 = (lt % nn) * 256;
; #pragma unroll
;         for (int i = 0; i < 8; ++i) rg[i] = *(const f32x4*)(src + (size_t)(k0 + kr + 8 * i) * N + n0 + c4 * 4);
;     }
;     while (have) {
; #pragma unroll
;         for (int i = 0; i < 8; ++i) { LAS float* q = tl + (kr + 8 * i) * 257 + c4 * 4; q[0] = rg[i][0]; q[1] = rg[i][1]; q[2] = rg[i][2]; q[3] = rg[i][3]; }
;         __syncthreads();
;         bf16_t* cdst = dst; const float* cgain = gain; const int cK = K, ck0 = k0, cn0 = n0;
;         tile += G; have = tile < NT_CONV;
;         if (have) {
;             wjob(p, tile, src, dst, gain, K, N, lt);
;             const int nn = N >> 8; k0 = (lt / nn) * 64; n0 = (lt % nn) * 256;
; #pragma unroll
;             for (int i = 0; i < 8; ++i) rg[i] = *(const f32x4*)(src + (size_t)(k0 + kr + 8 * i) * N + n0 + c4 * 4);
;         }
;         const int kq = tid & 7;
;         f32x4 g0 = (f32x4){1.f, 1.f, 1.f, 1.f}, g1 = g0;
;         if (cgain) { g0 = *(const f32x4*)(cgain + ck0 + kq * 8); g1 = *(const f32x4*)(cgain + ck0 + kq * 8 + 4); }
; #pragma unroll
;         for (int pass = 0; pass < 4; ++pass) {
;             const int n = (tid >> 3) + 64 * pass;
;             const LAS float* q = tl + (kq * 8) * 257 + n;
.LBB0_74:
	s_add_u32 s45, s28, 0x1384000
	s_addc_u32 s69, s29, 0
	s_add_u32 s70, s28, 0x7784000
	s_addc_u32 s71, s29, 0
	v_and_b32_e32 v36, 7, v34
	s_movk_i32 s34, 0x404
	s_cmp_eq_u64 s[22:23], 0
	v_lshlrev_b32_e32 v46, 3, v36
	v_ashrrev_i32_e32 v47, 3, v34
	v_mul_u32_u24_e32 v34, 0x2020, v36
	v_mul_lo_u32 v36, v43, s34
	s_cselect_b64 s[34:35], -1, 0
	s_add_u32 s72, s28, 0xf784000
	s_addc_u32 s73, s29, 0
	s_add_u32 s74, s28, 0x4f84000
	s_addc_u32 s75, s29, 0
	s_add_u32 s36, s10, 0x4000
	s_addc_u32 s37, s11, 0
	s_cmp_eq_u64 s[10:11], 0
	s_cselect_b64 s[38:39], -1, 0
	s_add_u32 s76, s28, 0x2784000
	s_addc_u32 s77, s29, 0
	s_add_u32 s78, s28, 0x3784000
	s_addc_u32 s79, s29, 0
	s_add_u32 s40, s10, 0x2000
	s_addc_u32 s41, s11, 0
	s_add_u32 s80, s28, 0x4784000
	s_addc_u32 s81, s29, 0
	s_add_u32 s82, s28, 0x7384000
	s_mov_b32 s88, s83
	v_lshl_add_u32 v35, v1, 4, 0
	s_addc_u32 s83, s29, 0
	v_lshlrev_b32_e32 v37, 2, v47
	s_add_u32 s42, s28, 0x2384000
	v_add_u32_e32 v51, v35, v36
	v_mov_b32_e32 v45, 0
	v_add3_u32 v50, 0, v34, v37
	v_lshrrev_b32_e32 v128, 6, v166
	v_and_b32_e32 v129, 63, v166
	v_mul_u32_u24_e32 v128, 0x484, v128
	v_lshrrev_b32_e32 v130, 3, v129
	v_lshl_add_u32 v128, v129, 4, v128
	v_lshl_add_u32 v51, v130, 2, v128
	v_and_b32_e32 v128, 7, v166
	v_lshrrev_b32_e32 v129, 3, v166
	v_lshrrev_b32_e32 v130, 8, v166
	v_mul_u32_u24_e32 v128, 0x2420, v128
	v_add_u32_e32 v129, v129, v130
	v_lshl_add_u32 v50, v129, 2, v128
	s_addc_u32 s43, s29, 0
	v_add_u32_e32 v52, 0x2420, v51
	v_add_u32_e32 v53, 0x2428, v51
	v_add_u32_e32 v54, 0x4840, v51
	v_add_u32_e32 v55, 0x4848, v51
	v_add_u32_e32 v56, 0x6c60, v51
	v_add_u32_e32 v57, 0x6c68, v51
	v_add_u32_e32 v58, 0x9080, v51
	v_add_u32_e32 v59, 0x9088, v51
	v_add_u32_e32 v60, 0xb4a0, v51
	v_add_u32_e32 v61, 0xb4a8, v51
	v_add_u32_e32 v62, 0xd8c0, v51
	v_add_u32_e32 v63, 0xd8c8, v51
	v_add_u32_e32 v64, 0xfce0, v51
	v_add_u32_e32 v65, 0xfce8, v51
	v_lshlrev_b32_e32 v48, 2, v42
	v_lshlrev_b32_e32 v44, 1, v46
	s_mov_b32 s84, s66
	s_branch .LBB0_77

; #define LAS __attribute__((address_space(3)))
; __device__ __forceinline__ unsigned cvt_pk_bf16(float lo, float hi) { unsigned r; asm volatile("v_cvt_pk_bf16_f32 %0, %1, %2" : "=v"(r) : "v"(lo), "v"(hi)); return r; }
; __device__ __forceinline__ void convert_phase(const Params& p, LAS unsigned char* lds) {
;     ...
;         const int kq = tid & 7;
;         f32x4 g0 = (f32x4){1.f, 1.f, 1.f, 1.f}, g1 = g0;
;         if (cgain) { g0 = *(const f32x4*)(cgain + ck0 + kq * 8); g1 = *(const f32x4*)(cgain + ck0 + kq * 8 + 4); }
; #pragma unroll
;         for (int pass = 0; pass < 4; ++pass) {
;             const int n = (tid >> 3) + 64 * pass;
;             const LAS float* q = tl + (kq * 8) * 257 + n;
;             u32x4 w; w.x = cvt_pk_bf16(q[0] * g0[0], q[257] * g0[1]); w.y = cvt_pk_bf16(q[2 * 257] * g0[2], q[3 * 257] * g0[3]);
;             w.z = cvt_pk_bf16(q[4 * 257] * g1[0], q[5 * 257] * g1[1]); w.w = cvt_pk_bf16(q[6 * 257] * g1[2], q[7 * 257] * g1[3]);
;             *(u32x4*)(cdst + (size_t)(cn0 + n) * cK + ck0 + kq * 8) = w;
;         }
;         __syncthreads();
.LBB0_76:
	ds_read_b32 v49, v50
	ds_read_b32 v66, v50 offset:1156
	s_lshl_b64 s[0:1], s[46:47], 1
	s_add_u32 s0, s30, s0
	v_add_u32_e32 v76, s44, v47
	s_waitcnt vmcnt(1) lgkmcnt(1)
	v_mul_f32_e32 v49, v38, v49
	s_waitcnt lgkmcnt(0)
	v_mul_f32_e32 v66, v39, v66
	v_cvt_pk_bf16_f32 v66, v49, v66
	ds_read_b32 v49, v50 offset:2312
	ds_read_b32 v67, v50 offset:3468
	s_addc_u32 s1, s31, s1
	v_lshl_add_u64 v[70:71], s[0:1], 0, v[44:45]
	v_mad_u64_u32 v[72:73], s[0:1], s67, v76, 0
	s_waitcnt lgkmcnt(1)
	v_mul_f32_e32 v49, v40, v49
	s_waitcnt lgkmcnt(0)
	v_mul_f32_e32 v67, v41, v67
	v_cvt_pk_bf16_f32 v67, v49, v67
	ds_read_b32 v49, v50 offset:4624
	ds_read_b32 v68, v50 offset:5780
	v_mov_b32_e32 v74, v73
	s_andn2_b64 vcc, exec, s[48:49]
	s_mov_b32 s46, s58
	s_waitcnt vmcnt(0) lgkmcnt(1)
	v_mul_f32_e32 v49, v34, v49
	s_waitcnt lgkmcnt(0)
	v_mul_f32_e32 v68, v35, v68
	v_cvt_pk_bf16_f32 v68, v49, v68
	ds_read_b32 v49, v50 offset:6936
	ds_read_b32 v69, v50 offset:8092
	s_mov_b32 s44, s56
	s_mov_b64 s[30:31], s[54:55]
	s_waitcnt lgkmcnt(1)
	v_mul_f32_e32 v49, v36, v49
	s_waitcnt lgkmcnt(0)
	v_mul_f32_e32 v69, v37, v69
	v_cvt_pk_bf16_f32 v69, v49, v69
	v_ashrrev_i32_e32 v49, 31, v76
	v_mad_u64_u32 v[74:75], s[0:1], s67, v49, v[74:75]
	ds_read_b32 v49, v50 offset:264
	ds_read_b32 v75, v50 offset:1420
	v_mov_b32_e32 v73, v74
	v_lshl_add_u64 v[72:73], v[72:73], 1, v[70:71]
	global_store_dwordx4 v[72:73], v[66:69], off
	s_waitcnt lgkmcnt(1)
	v_mul_f32_e32 v49, v38, v49
	s_waitcnt lgkmcnt(0)
	v_mul_f32_e32 v66, v39, v75
	v_cvt_pk_bf16_f32 v66, v49, v66
	ds_read_b32 v49, v50 offset:2576
	ds_read_b32 v67, v50 offset:3732
	s_waitcnt lgkmcnt(1)
	v_mul_f32_e32 v49, v40, v49
	s_waitcnt lgkmcnt(0)
	v_mul_f32_e32 v67, v41, v67
	v_cvt_pk_bf16_f32 v67, v49, v67
	ds_read_b32 v49, v50 offset:4888
	ds_read_b32 v68, v50 offset:6044
	s_waitcnt lgkmcnt(1)
	v_mul_f32_e32 v49, v34, v49
	s_waitcnt lgkmcnt(0)
	v_mul_f32_e32 v68, v35, v68
	v_cvt_pk_bf16_f32 v68, v49, v68
	ds_read_b32 v49, v50 offset:7200
	ds_read_b32 v69, v50 offset:8356
	s_waitcnt lgkmcnt(1)
	v_mul_f32_e32 v49, v36, v49
	s_waitcnt lgkmcnt(0)
	v_mul_f32_e32 v69, v37, v69
	v_cvt_pk_bf16_f32 v69, v49, v69
	v_add_u32_e32 v49, 64, v76
	v_mad_u64_u32 v[72:73], s[0:1], s67, v49, 0
	v_ashrrev_i32_e32 v75, 31, v49
	v_mov_b32_e32 v74, v73
	v_mad_u64_u32 v[74:75], s[0:1], s67, v75, v[74:75]
	ds_read_b32 v49, v50 offset:528
	ds_read_b32 v75, v50 offset:1684
	v_mov_b32_e32 v73, v74
	v_lshl_add_u64 v[72:73], v[72:73], 1, v[70:71]
	global_store_dwordx4 v[72:73], v[66:69], off
	s_waitcnt lgkmcnt(1)
	v_mul_f32_e32 v49, v38, v49
	s_waitcnt lgkmcnt(0)
	v_mul_f32_e32 v66, v39, v75
	v_cvt_pk_bf16_f32 v66, v49, v66
	ds_read_b32 v49, v50 offset:2840
	ds_read_b32 v67, v50 offset:3996
	s_waitcnt lgkmcnt(1)
	v_mul_f32_e32 v49, v40, v49
	s_waitcnt lgkmcnt(0)
	v_mul_f32_e32 v67, v41, v67
	v_cvt_pk_bf16_f32 v67, v49, v67
	ds_read_b32 v49, v50 offset:5152
	ds_read_b32 v68, v50 offset:6308
	s_waitcnt lgkmcnt(1)
	v_mul_f32_e32 v49, v34, v49
	s_waitcnt lgkmcnt(0)
	v_mul_f32_e32 v68, v35, v68
	v_cvt_pk_bf16_f32 v68, v49, v68
	ds_read_b32 v49, v50 offset:7464
	ds_read_b32 v69, v50 offset:8620
	s_waitcnt lgkmcnt(1)
	v_mul_f32_e32 v49, v36, v49
	s_waitcnt lgkmcnt(0)
	v_mul_f32_e32 v69, v37, v69
	v_cvt_pk_bf16_f32 v69, v49, v69
	v_add_u32_e32 v49, 0x80, v76
	v_mad_u64_u32 v[72:73], s[0:1], s67, v49, 0
	v_ashrrev_i32_e32 v75, 31, v49
	v_mov_b32_e32 v74, v73
	v_mad_u64_u32 v[74:75], s[0:1], s67, v75, v[74:75]
	ds_read_b32 v49, v50 offset:792
	ds_read_b32 v75, v50 offset:1948
	v_mov_b32_e32 v73, v74
	v_lshl_add_u64 v[72:73], v[72:73], 1, v[70:71]
	global_store_dwordx4 v[72:73], v[66:69], off
	s_waitcnt lgkmcnt(1)
	v_mul_f32_e32 v38, v38, v49
	s_waitcnt lgkmcnt(0)
	v_mul_f32_e32 v39, v39, v75
	v_cvt_pk_bf16_f32 v38, v38, v39
	ds_read_b32 v39, v50 offset:3104
	ds_read_b32 v49, v50 offset:4260
	s_waitcnt lgkmcnt(1)
	v_mul_f32_e32 v39, v40, v39
	s_waitcnt lgkmcnt(0)
	v_mul_f32_e32 v40, v41, v49
	v_cvt_pk_bf16_f32 v39, v39, v40
	ds_read_b32 v40, v50 offset:5416
	ds_read_b32 v41, v50 offset:6572
	s_waitcnt lgkmcnt(1)
	v_mul_f32_e32 v34, v34, v40
	s_waitcnt lgkmcnt(0)
	v_mul_f32_e32 v35, v35, v41
	v_cvt_pk_bf16_f32 v40, v34, v35
	ds_read_b32 v34, v50 offset:7728
	ds_read_b32 v35, v50 offset:8884
	s_waitcnt lgkmcnt(1)
	v_mul_f32_e32 v34, v36, v34
	s_waitcnt lgkmcnt(0)
	v_mul_f32_e32 v35, v37, v35
	v_cvt_pk_bf16_f32 v41, v34, v35
	v_add_u32_e32 v34, 0xc0, v76
	v_ashrrev_i32_e32 v37, 31, v34
	v_mad_u64_u32 v[34:35], s[0:1], s67, v34, 0
	v_mov_b32_e32 v36, v35
	v_mad_u64_u32 v[36:37], s[0:1], s67, v37, v[36:37]
	v_mov_b32_e32 v35, v36
	v_lshl_add_u64 v[34:35], v[34:35], 1, v[70:71]
	s_mov_b32 s67, s85
	s_mov_b64 s[0:1], s[50:51]
	global_store_dwordx4 v[34:35], v[38:41], off
	s_barrier
	s_cbranch_vccz .LBB0_133
